# row passes a,b: additionally the once-read bf16 sublayer-output loads marked nt
# baseline (speedup 1.0000x reference)
.LBB0_289:
	v_lshl_add_u64 v[0:1], s[16:17], 0, v[192:193]
	v_add_co_u32_e32 v4, vcc, 0x1000, v0
	v_lshl_add_u64 v[32:33], s[20:21], 0, v[52:53]
	s_nop 0
	v_addc_co_u32_e32 v5, vcc, 0, v1, vcc
	v_add_co_u32_e32 v34, vcc, 0x1ba00000, v32
	global_load_dwordx4 v[8:11], v[0:1], off offset:16 nt
	global_load_dwordx4 v[12:15], v[0:1], off nt
	global_load_dwordx4 v[16:19], v[0:1], off offset:2064 nt
	global_load_dwordx4 v[20:23], v[0:1], off offset:2048 nt
	v_lshl_add_u64 v[2:3], v[0:1], 0, s[28:29]
	v_lshl_add_u64 v[0:1], v[0:1], 0, s[26:27]
	v_addc_co_u32_e32 v35, vcc, 0, v33, vcc
	global_load_dwordx4 v[28:31], v[4:5], off nt
	global_load_dwordx4 v[24:27], v[2:3], off offset:16 nt
	s_nop 0
	global_load_dwordx4 v[4:7], v[4:5], off offset:2048 nt
	s_nop 0
	global_load_dwordx4 v[0:3], v[0:1], off offset:16 nt
	s_nop 0
	global_load_dwordx4 v[64:67], v[34:35], off nt
	global_load_dwordx4 v[68:71], v[34:35], off offset:1024 nt
	global_load_dwordx4 v[58:61], v[34:35], off offset:2048 nt
	global_load_dwordx4 v[88:91], v[34:35], off offset:3072 nt
	s_mov_b32 s4, 0xf800000
	s_waitcnt vmcnt(3)
	v_and_b32_e32 v75, 0xffff0000, v66
	v_and_b32_e32 v74, 0xffff0000, v64
	v_and_b32_e32 v79, 0xffff0000, v67
	v_and_b32_e32 v78, 0xffff0000, v65
	v_lshlrev_b32_e32 v73, 16, v66
	v_lshlrev_b32_e32 v72, 16, v64
	v_lshlrev_b32_e32 v77, 16, v67
	v_lshlrev_b32_e32 v76, 16, v65
	v_pk_mul_f32 v[34:35], v[74:75], v[74:75]
	v_pk_mul_f32 v[64:65], v[78:79], v[78:79]
	v_pk_fma_f32 v[34:35], v[72:73], v[72:73], v[34:35]
	v_pk_fma_f32 v[64:65], v[76:77], v[76:77], v[64:65]
	s_waitcnt vmcnt(2)
	v_lshlrev_b32_e32 v32, 16, v70
	v_pk_add_f32 v[34:35], v[34:35], v[64:65]
	v_and_b32_e32 v33, 0xffff0000, v70
	v_pk_add_f32 v[64:65], v[34:35], v[34:35] op_sel_hi:[0,1]
	v_lshlrev_b32_e32 v35, 16, v69
	v_lshlrev_b32_e32 v34, 16, v68
	v_and_b32_e32 v69, 0xffff0000, v69
	v_and_b32_e32 v68, 0xffff0000, v68
	s_waitcnt vmcnt(1)
	v_lshlrev_b32_e32 v36, 16, v58
	v_pk_mul_f32 v[66:67], v[68:69], v[68:69]
	v_lshlrev_b32_e32 v70, 16, v71
	s_waitcnt vmcnt(0)
	v_lshlrev_b32_e32 v56, 16, v90
	v_and_b32_e32 v85, 0xffff0000, v90
	v_lshlrev_b32_e32 v54, 16, v91
	v_and_b32_e32 v55, 0xffff0000, v91
	v_pk_fma_f32 v[66:67], v[34:35], v[34:35], v[66:67]
	v_mul_f32_e32 v37, v32, v32
	v_mul_f32_e32 v91, v33, v33
	v_and_b32_e32 v71, 0xffff0000, v71
	v_mul_f32_e32 v62, v70, v70
	v_mov_b32_e32 v90, v36
	v_and_b32_e32 v86, 0xffff0000, v58
	v_lshlrev_b32_e32 v38, 16, v59
	v_and_b32_e32 v39, 0xffff0000, v59
	v_pk_add_f32 v[66:67], v[66:67], v[66:67] op_sel_hi:[0,1]
	v_pk_fma_f32 v[92:93], v[70:71], v[70:71], v[62:63] op_sel_hi:[1,1,0]
	v_pk_add_f32 v[90:91], v[36:37], v[90:91]
	v_mul_f32_e32 v92, v86, v86
	v_mul_f32_e32 v64, v38, v38
	v_mul_f32_e32 v66, v39, v39
	v_mul_f32_e32 v94, v36, v36
	v_mov_b32_e32 v95, v91
	v_pk_add_f32 v[90:91], v[94:95], v[92:93]
	v_pk_add_f32 v[64:65], v[64:65], v[66:67]
	v_and_b32_e32 v67, 0xffff0000, v61
	v_pk_add_f32 v[64:65], v[90:91], v[64:65]
	v_and_b32_e32 v66, 0xffff0000, v60
	v_pk_add_f32 v[90:91], v[64:65], v[64:65] op_sel_hi:[0,1]
	v_lshlrev_b32_e32 v65, 16, v61
	v_lshlrev_b32_e32 v64, 16, v60
	v_pk_mul_f32 v[60:61], v[66:67], v[66:67]
	v_lshlrev_b32_e32 v58, 16, v88
	v_pk_fma_f32 v[60:61], v[64:65], v[64:65], v[60:61]
	v_and_b32_e32 v59, 0xffff0000, v88
	v_pk_add_f32 v[92:93], v[60:61], v[60:61] op_sel_hi:[0,1]
	v_lshlrev_b32_e32 v60, 16, v89
	v_mul_f32_e32 v57, v58, v58
	v_mul_f32_e32 v95, v59, v59
	v_and_b32_e32 v61, 0xffff0000, v89
	v_mul_f32_e32 v62, v60, v60
	v_mov_b32_e32 v94, v56
	v_pk_fma_f32 v[88:89], v[60:61], v[60:61], v[62:63] op_sel_hi:[1,1,0]
	v_pk_add_f32 v[94:95], v[56:57], v[94:95]
	v_mul_f32_e32 v88, v85, v85
	v_mul_f32_e32 v92, v54, v54
	v_mul_f32_e32 v90, v55, v55
	v_mul_f32_e32 v96, v56, v56
	v_mov_b32_e32 v97, v95
	v_pk_add_f32 v[88:89], v[96:97], v[88:89]
	v_pk_add_f32 v[90:91], v[92:93], v[90:91]
	v_mov_b32_e32 v96, v72
	v_pk_add_f32 v[88:89], v[88:89], v[90:91]
	v_mov_b32_e32 v97, v74
	v_add_f32_e32 v37, v88, v89
	ds_bpermute_b32 v57, v63, v37
	v_mov_b32_e32 v74, v73
	s_waitcnt lgkmcnt(0)
	v_add_f32_e32 v37, v37, v57
	ds_bpermute_b32 v57, v80, v37
	s_waitcnt lgkmcnt(0)
	v_add_f32_e32 v37, v37, v57
	ds_bpermute_b32 v57, v81, v37
	s_waitcnt lgkmcnt(0)
	v_add_f32_e32 v37, v37, v57
	ds_bpermute_b32 v57, v82, v37
	s_waitcnt lgkmcnt(0)
	v_add_f32_e32 v37, v37, v57
	ds_bpermute_b32 v57, v83, v37
	s_waitcnt lgkmcnt(0)
	v_add_f32_e32 v37, v37, v57
	ds_bpermute_b32 v57, v84, v37
	s_waitcnt lgkmcnt(0)
	v_add_f32_e32 v37, v37, v57
	v_fmamk_f32 v37, v37, 0x3a000000, v219
	v_cmp_gt_f32_e32 vcc, s4, v37
	v_mul_f32_e32 v57, 0x4f800000, v37
	s_nop 0
	v_cndmask_b32_e32 v37, v37, v57, vcc
	v_sqrt_f32_e32 v57, v37
	s_nop 0
	v_add_u32_e32 v62, -1, v57
	v_fma_f32 v87, -v62, v57, v37
	v_cmp_ge_f32_e64 s[6:7], 0, v87
	v_add_u32_e32 v87, 1, v57
	s_nop 0
	v_cndmask_b32_e64 v62, v57, v62, s[6:7]
	v_fma_f32 v57, -v87, v57, v37
	v_cmp_lt_f32_e64 s[6:7], 0, v57
	s_nop 1
	v_cndmask_b32_e64 v57, v62, v87, s[6:7]
	v_mul_f32_e32 v62, 0x37800000, v57
	v_cndmask_b32_e32 v57, v57, v62, vcc
	v_cmp_class_f32_e32 vcc, v37, v220
	s_nop 1
	v_cndmask_b32_e32 v37, v57, v37, vcc
	v_div_scale_f32 v57, s[4:5], v37, v37, 0.5
	v_rcp_f32_e32 v62, v57
	s_nop 0
	v_fma_f32 v87, -v57, v62, 1.0
	v_fmac_f32_e32 v62, v87, v62
	v_div_scale_f32 v87, vcc, 0.5, v37, 0.5
	v_mul_f32_e32 v88, v87, v62
	v_fma_f32 v89, -v57, v88, v87
	v_fmac_f32_e32 v88, v89, v62
	v_fma_f32 v57, -v57, v88, v87
	v_div_fmas_f32 v57, v57, v62, v88
	v_mov_b64_e32 v[88:89], v[100:101]
	v_mov_b64_e32 v[90:91], v[102:103]
	v_mov_b64_e32 v[92:93], v[104:105]
	v_mov_b64_e32 v[94:95], v[106:107]
	v_div_fixup_f32 v62, v57, v37, 0.5
	v_mov_b32_e32 v37, v86
	v_mov_b32_e32 v57, v85
	s_andn2_b64 vcc, exec, s[10:11]
	v_pk_mul_f32 v[72:73], v[88:89], v[74:75]
	v_pk_mul_f32 v[92:93], v[92:93], v[96:97]
	v_mov_b32_e32 v97, v78
	v_mov_b32_e32 v78, v77
	v_pk_mul_f32 v[74:75], v[90:91], v[78:79]
	v_mov_b32_e32 v96, v76
	v_pk_fma_f32 v[10:11], v[74:75], v[62:63], v[10:11] op_sel_hi:[1,0,1]
	v_pk_fma_f32 v[8:9], v[72:73], v[62:63], v[8:9] op_sel_hi:[1,0,1]
	v_mov_b64_e32 v[72:73], v[108:109]
	v_mov_b64_e32 v[74:75], v[110:111]
	v_mov_b64_e32 v[76:77], v[112:113]
	v_mov_b64_e32 v[78:79], v[114:115]
	v_mov_b32_e32 v89, v68
	v_mov_b32_e32 v68, v35
	v_mov_b32_e32 v88, v34
	v_pk_mul_f32 v[94:95], v[94:95], v[96:97]
	v_pk_fma_f32 v[12:13], v[92:93], v[62:63], v[12:13] op_sel_hi:[1,0,1]
	v_pk_fma_f32 v[14:15], v[94:95], v[62:63], v[14:15] op_sel_hi:[1,0,1]
	v_pk_mul_f32 v[32:33], v[72:73], v[32:33]
	v_pk_mul_f32 v[34:35], v[78:79], v[68:69]
	v_pk_fma_f32 v[16:17], v[32:33], v[62:63], v[16:17] op_sel_hi:[1,0,1]
	v_pk_fma_f32 v[22:23], v[34:35], v[62:63], v[22:23] op_sel_hi:[1,0,1]
	v_pk_mul_f32 v[34:35], v[74:75], v[70:71]
	v_pk_mul_f32 v[76:77], v[76:77], v[88:89]
	v_pk_fma_f32 v[18:19], v[34:35], v[62:63], v[18:19] op_sel_hi:[1,0,1]
	v_mov_b64_e32 v[32:33], v[116:117]
	v_mov_b64_e32 v[34:35], v[118:119]
	v_mov_b64_e32 v[68:69], v[120:121]
	v_mov_b64_e32 v[70:71], v[122:123]
	v_pk_fma_f32 v[20:21], v[76:77], v[62:63], v[20:21] op_sel_hi:[1,0,1]
	v_pk_mul_f32 v[36:37], v[68:69], v[36:37]
	s_nop 0
	v_pk_fma_f32 v[28:29], v[36:37], v[62:63], v[28:29] op_sel_hi:[1,0,1]
	v_mov_b32_e32 v36, v64
	v_mov_b32_e32 v37, v66
	v_mov_b32_e32 v66, v65
	v_pk_mul_f32 v[38:39], v[70:71], v[38:39]
	v_pk_mul_f32 v[32:33], v[32:33], v[36:37]
	v_pk_mul_f32 v[34:35], v[34:35], v[66:67]
	v_pk_fma_f32 v[30:31], v[38:39], v[62:63], v[30:31] op_sel_hi:[1,0,1]
	v_pk_fma_f32 v[26:27], v[34:35], v[62:63], v[26:27] op_sel_hi:[1,0,1]
	v_pk_fma_f32 v[24:25], v[32:33], v[62:63], v[24:25] op_sel_hi:[1,0,1]
	v_mov_b64_e32 v[32:33], v[124:125]
	v_mov_b64_e32 v[34:35], v[126:127]
	v_mov_b64_e32 v[36:37], v[128:129]
	v_mov_b64_e32 v[38:39], v[130:131]
	v_pk_mul_f32 v[32:33], v[32:33], v[56:57]
	v_pk_mul_f32 v[36:37], v[36:37], v[58:59]
	v_pk_mul_f32 v[38:39], v[38:39], v[60:61]
	v_pk_mul_f32 v[34:35], v[34:35], v[54:55]
	v_pk_fma_f32 v[6:7], v[38:39], v[62:63], v[6:7] op_sel_hi:[1,0,1]
	v_pk_fma_f32 v[4:5], v[36:37], v[62:63], v[4:5] op_sel_hi:[1,0,1]
	v_pk_fma_f32 v[2:3], v[34:35], v[62:63], v[2:3] op_sel_hi:[1,0,1]
	v_pk_fma_f32 v[0:1], v[32:33], v[62:63], v[0:1] op_sel_hi:[1,0,1]
	s_cbranch_vccnz .LBB0_291
	v_lshl_add_u64 v[32:33], s[22:23], 0, v[192:193]
	global_store_dwordx4 v[32:33], v[12:15], off nt
	global_store_dwordx4 v[32:33], v[8:11], off offset:16 nt
	global_store_dwordx4 v[32:33], v[20:23], off offset:2048 nt
	global_store_dwordx4 v[32:33], v[16:19], off offset:2064 nt
	v_add_co_u32_e32 v32, vcc, 0x1000, v32
	s_nop 1
	v_addc_co_u32_e32 v33, vcc, 0, v33, vcc
	global_store_dwordx4 v[32:33], v[28:31], off nt
	global_store_dwordx4 v[32:33], v[24:27], off offset:16 nt
	global_store_dwordx4 v[32:33], v[4:7], off offset:2048 nt
	global_store_dwordx4 v[32:33], v[0:3], off offset:2064 nt

.LBB0_746:
	v_lshl_add_u64 v[0:1], s[12:13], 0, v[192:193]
	v_add_co_u32_e32 v4, vcc, 0x1000, v0
	v_lshl_add_u64 v[32:33], s[16:17], 0, v[52:53]
	s_nop 0
	v_addc_co_u32_e32 v5, vcc, 0, v1, vcc
	v_add_co_u32_e32 v34, vcc, 0x1ba00000, v32
	global_load_dwordx4 v[8:11], v[0:1], off offset:16 nt
	global_load_dwordx4 v[12:15], v[0:1], off nt
	global_load_dwordx4 v[16:19], v[0:1], off offset:2064 nt
	global_load_dwordx4 v[20:23], v[0:1], off offset:2048 nt
	v_lshl_add_u64 v[2:3], v[0:1], 0, s[26:27]
	v_lshl_add_u64 v[0:1], v[0:1], 0, s[24:25]
	v_addc_co_u32_e32 v35, vcc, 0, v33, vcc
	global_load_dwordx4 v[28:31], v[4:5], off nt
	global_load_dwordx4 v[24:27], v[2:3], off offset:16 nt
	s_nop 0
	global_load_dwordx4 v[4:7], v[4:5], off offset:2048 nt
	s_nop 0
	global_load_dwordx4 v[0:3], v[0:1], off offset:16 nt
	s_nop 0
	global_load_dwordx4 v[64:67], v[34:35], off nt
	global_load_dwordx4 v[68:71], v[34:35], off offset:1024 nt
	global_load_dwordx4 v[58:61], v[34:35], off offset:2048 nt
	global_load_dwordx4 v[82:85], v[34:35], off offset:3072 nt
	s_mov_b32 s4, 0xf800000
	s_waitcnt vmcnt(3)
	v_and_b32_e32 v75, 0xffff0000, v66
	v_and_b32_e32 v74, 0xffff0000, v64
	v_and_b32_e32 v79, 0xffff0000, v67
	v_and_b32_e32 v78, 0xffff0000, v65
	v_lshlrev_b32_e32 v73, 16, v66
	v_lshlrev_b32_e32 v72, 16, v64
	v_lshlrev_b32_e32 v77, 16, v67
	v_lshlrev_b32_e32 v76, 16, v65
	v_pk_mul_f32 v[34:35], v[74:75], v[74:75]
	v_pk_mul_f32 v[64:65], v[78:79], v[78:79]
	v_pk_fma_f32 v[34:35], v[72:73], v[72:73], v[34:35]
	v_pk_fma_f32 v[64:65], v[76:77], v[76:77], v[64:65]
	s_waitcnt vmcnt(2)
	v_lshlrev_b32_e32 v32, 16, v70
	v_pk_add_f32 v[34:35], v[34:35], v[64:65]
	v_and_b32_e32 v33, 0xffff0000, v70
	v_pk_add_f32 v[64:65], v[34:35], v[34:35] op_sel_hi:[0,1]
	v_lshlrev_b32_e32 v35, 16, v69
	v_lshlrev_b32_e32 v34, 16, v68
	v_and_b32_e32 v69, 0xffff0000, v69
	v_and_b32_e32 v68, 0xffff0000, v68
	s_waitcnt vmcnt(1)
	v_lshlrev_b32_e32 v36, 16, v58
	v_pk_mul_f32 v[66:67], v[68:69], v[68:69]
	v_lshlrev_b32_e32 v70, 16, v71
	s_waitcnt vmcnt(0)
	v_lshlrev_b32_e32 v56, 16, v84
	v_and_b32_e32 v63, 0xffff0000, v84
	v_lshlrev_b32_e32 v54, 16, v85
	v_and_b32_e32 v55, 0xffff0000, v85
	v_pk_fma_f32 v[66:67], v[34:35], v[34:35], v[66:67]
	v_mul_f32_e32 v37, v32, v32
	v_mul_f32_e32 v85, v33, v33
	v_and_b32_e32 v71, 0xffff0000, v71
	v_mul_f32_e32 v62, v70, v70
	v_mov_b32_e32 v84, v36
	v_and_b32_e32 v80, 0xffff0000, v58
	v_lshlrev_b32_e32 v38, 16, v59
	v_and_b32_e32 v39, 0xffff0000, v59
	v_pk_add_f32 v[66:67], v[66:67], v[66:67] op_sel_hi:[0,1]
	v_pk_fma_f32 v[86:87], v[70:71], v[70:71], v[62:63] op_sel_hi:[1,1,0]
	v_pk_add_f32 v[84:85], v[36:37], v[84:85]
	v_mul_f32_e32 v86, v80, v80
	v_mul_f32_e32 v64, v38, v38
	v_mul_f32_e32 v66, v39, v39
	v_mul_f32_e32 v88, v36, v36
	v_mov_b32_e32 v89, v85
	v_pk_add_f32 v[84:85], v[88:89], v[86:87]
	v_pk_add_f32 v[64:65], v[64:65], v[66:67]
	v_and_b32_e32 v67, 0xffff0000, v61
	v_pk_add_f32 v[64:65], v[84:85], v[64:65]
	v_and_b32_e32 v66, 0xffff0000, v60
	v_pk_add_f32 v[84:85], v[64:65], v[64:65] op_sel_hi:[0,1]
	v_lshlrev_b32_e32 v65, 16, v61
	v_lshlrev_b32_e32 v64, 16, v60
	v_pk_mul_f32 v[60:61], v[66:67], v[66:67]
	v_lshlrev_b32_e32 v58, 16, v82
	v_pk_fma_f32 v[60:61], v[64:65], v[64:65], v[60:61]
	v_and_b32_e32 v59, 0xffff0000, v82
	v_pk_add_f32 v[86:87], v[60:61], v[60:61] op_sel_hi:[0,1]
	v_lshlrev_b32_e32 v60, 16, v83
	v_mul_f32_e32 v57, v58, v58
	v_mul_f32_e32 v89, v59, v59
	v_and_b32_e32 v61, 0xffff0000, v83
	v_mul_f32_e32 v62, v60, v60
	v_mov_b32_e32 v88, v56
	v_pk_fma_f32 v[82:83], v[60:61], v[60:61], v[62:63] op_sel_hi:[1,1,0]
	v_pk_add_f32 v[88:89], v[56:57], v[88:89]
	v_mul_f32_e32 v82, v63, v63
	v_mul_f32_e32 v86, v54, v54
	v_mul_f32_e32 v84, v55, v55
	v_mul_f32_e32 v90, v56, v56
	v_mov_b32_e32 v91, v89
	v_pk_add_f32 v[82:83], v[90:91], v[82:83]
	v_pk_add_f32 v[84:85], v[86:87], v[84:85]
	v_mov_b32_e32 v90, v72
	v_pk_add_f32 v[82:83], v[82:83], v[84:85]
	v_mov_b32_e32 v91, v74
	v_add_f32_e32 v37, v82, v83
	ds_bpermute_b32 v57, v230, v37
	v_mov_b32_e32 v74, v73
	s_waitcnt lgkmcnt(0)
	v_add_f32_e32 v37, v37, v57
	ds_bpermute_b32 v57, v231, v37
	s_waitcnt lgkmcnt(0)
	v_add_f32_e32 v37, v37, v57
	ds_bpermute_b32 v57, v232, v37
	s_waitcnt lgkmcnt(0)
	v_add_f32_e32 v37, v37, v57
	ds_bpermute_b32 v57, v233, v37
	s_waitcnt lgkmcnt(0)
	v_add_f32_e32 v37, v37, v57
	ds_bpermute_b32 v57, v234, v37
	s_waitcnt lgkmcnt(0)
	v_add_f32_e32 v37, v37, v57
	ds_bpermute_b32 v57, v235, v37
	s_waitcnt lgkmcnt(0)
	v_add_f32_e32 v37, v37, v57
	v_fmamk_f32 v37, v37, 0x3a000000, v219
	v_cmp_gt_f32_e32 vcc, s4, v37
	v_mul_f32_e32 v57, 0x4f800000, v37
	s_nop 0
	v_cndmask_b32_e32 v37, v37, v57, vcc
	v_sqrt_f32_e32 v57, v37
	s_nop 0
	v_add_u32_e32 v62, -1, v57
	v_fma_f32 v81, -v62, v57, v37
	v_cmp_ge_f32_e64 s[4:5], 0, v81
	v_add_u32_e32 v81, 1, v57
	s_nop 0
	v_cndmask_b32_e64 v62, v57, v62, s[4:5]
	v_fma_f32 v57, -v81, v57, v37
	v_cmp_lt_f32_e64 s[4:5], 0, v57
	s_nop 1
	v_cndmask_b32_e64 v57, v62, v81, s[4:5]
	v_mul_f32_e32 v62, 0x37800000, v57
	v_cndmask_b32_e32 v57, v57, v62, vcc
	v_cmp_class_f32_e32 vcc, v37, v220
	s_nop 1
	v_cndmask_b32_e32 v37, v57, v37, vcc
	v_div_scale_f32 v57, s[4:5], v37, v37, 1.0
	v_rcp_f32_e32 v62, v57
	s_nop 0
	v_fma_f32 v81, -v57, v62, 1.0
	v_fmac_f32_e32 v62, v81, v62
	v_div_scale_f32 v81, vcc, 1.0, v37, 1.0
	v_mul_f32_e32 v82, v81, v62
	v_fma_f32 v83, -v57, v82, v81
	v_fmac_f32_e32 v82, v83, v62
	v_fma_f32 v57, -v57, v82, v81
	v_div_fmas_f32 v57, v57, v62, v82
	v_mov_b64_e32 v[82:83], v[100:101]
	v_mov_b64_e32 v[84:85], v[102:103]
	v_mov_b64_e32 v[86:87], v[104:105]
	v_mov_b64_e32 v[88:89], v[106:107]
	v_div_fixup_f32 v62, v57, v37, 1.0
	v_mov_b32_e32 v37, v80
	v_mov_b32_e32 v57, v63
	s_andn2_b64 vcc, exec, s[8:9]
	v_pk_mul_f32 v[72:73], v[82:83], v[74:75]
	v_pk_mul_f32 v[86:87], v[86:87], v[90:91]
	v_mov_b32_e32 v91, v78
	v_mov_b32_e32 v78, v77
	v_pk_mul_f32 v[74:75], v[84:85], v[78:79]
	v_mov_b32_e32 v90, v76
	v_pk_fma_f32 v[10:11], v[74:75], v[62:63], v[10:11] op_sel_hi:[1,0,1]
	v_pk_fma_f32 v[8:9], v[72:73], v[62:63], v[8:9] op_sel_hi:[1,0,1]
	v_mov_b64_e32 v[72:73], v[108:109]
	v_mov_b64_e32 v[74:75], v[110:111]
	v_mov_b64_e32 v[76:77], v[112:113]
	v_mov_b64_e32 v[78:79], v[114:115]
	v_mov_b32_e32 v83, v68
	v_mov_b32_e32 v68, v35
	v_mov_b32_e32 v82, v34
	v_pk_mul_f32 v[88:89], v[88:89], v[90:91]
	v_pk_fma_f32 v[12:13], v[86:87], v[62:63], v[12:13] op_sel_hi:[1,0,1]
	v_pk_fma_f32 v[14:15], v[88:89], v[62:63], v[14:15] op_sel_hi:[1,0,1]
	v_pk_mul_f32 v[32:33], v[72:73], v[32:33]
	v_pk_mul_f32 v[34:35], v[78:79], v[68:69]
	v_pk_fma_f32 v[16:17], v[32:33], v[62:63], v[16:17] op_sel_hi:[1,0,1]
	v_pk_fma_f32 v[22:23], v[34:35], v[62:63], v[22:23] op_sel_hi:[1,0,1]
	v_pk_mul_f32 v[34:35], v[74:75], v[70:71]
	v_pk_mul_f32 v[76:77], v[76:77], v[82:83]
	v_pk_fma_f32 v[18:19], v[34:35], v[62:63], v[18:19] op_sel_hi:[1,0,1]
	v_mov_b64_e32 v[32:33], v[116:117]
	v_mov_b64_e32 v[34:35], v[118:119]
	v_mov_b64_e32 v[68:69], v[120:121]
	v_mov_b64_e32 v[70:71], v[122:123]
	v_pk_fma_f32 v[20:21], v[76:77], v[62:63], v[20:21] op_sel_hi:[1,0,1]
	v_pk_mul_f32 v[36:37], v[68:69], v[36:37]
	s_nop 0
	v_pk_fma_f32 v[28:29], v[36:37], v[62:63], v[28:29] op_sel_hi:[1,0,1]
	v_mov_b32_e32 v36, v64
	v_mov_b32_e32 v37, v66
	v_mov_b32_e32 v66, v65
	v_pk_mul_f32 v[38:39], v[70:71], v[38:39]
	v_pk_mul_f32 v[32:33], v[32:33], v[36:37]
	v_pk_mul_f32 v[34:35], v[34:35], v[66:67]
	v_pk_fma_f32 v[30:31], v[38:39], v[62:63], v[30:31] op_sel_hi:[1,0,1]
	v_pk_fma_f32 v[26:27], v[34:35], v[62:63], v[26:27] op_sel_hi:[1,0,1]
	v_pk_fma_f32 v[24:25], v[32:33], v[62:63], v[24:25] op_sel_hi:[1,0,1]
	v_mov_b64_e32 v[32:33], v[124:125]
	v_mov_b64_e32 v[34:35], v[126:127]
	v_mov_b64_e32 v[36:37], v[128:129]
	v_mov_b64_e32 v[38:39], v[130:131]
	v_pk_mul_f32 v[32:33], v[32:33], v[56:57]
	v_pk_mul_f32 v[36:37], v[36:37], v[58:59]
	v_pk_mul_f32 v[38:39], v[38:39], v[60:61]
	v_pk_mul_f32 v[34:35], v[34:35], v[54:55]
	v_pk_fma_f32 v[6:7], v[38:39], v[62:63], v[6:7] op_sel_hi:[1,0,1]
	v_pk_fma_f32 v[4:5], v[36:37], v[62:63], v[4:5] op_sel_hi:[1,0,1]
	v_pk_fma_f32 v[2:3], v[34:35], v[62:63], v[2:3] op_sel_hi:[1,0,1]
	v_pk_fma_f32 v[0:1], v[32:33], v[62:63], v[0:1] op_sel_hi:[1,0,1]
	s_cbranch_vccnz .LBB0_748
	v_lshl_add_u64 v[32:33], s[18:19], 0, v[192:193]
	global_store_dwordx4 v[32:33], v[12:15], off nt
	global_store_dwordx4 v[32:33], v[8:11], off offset:16 nt
	global_store_dwordx4 v[32:33], v[20:23], off offset:2048 nt
	global_store_dwordx4 v[32:33], v[16:19], off offset:2064 nt
	v_add_co_u32_e32 v32, vcc, 0x1000, v32
	s_nop 1
	v_addc_co_u32_e32 v33, vcc, 0, v33, vcc
	global_store_dwordx4 v[32:33], v[28:31], off nt
	global_store_dwordx4 v[32:33], v[24:27], off offset:16 nt
	global_store_dwordx4 v[32:33], v[4:7], off offset:2048 nt
	global_store_dwordx4 v[32:33], v[0:3], off offset:2064 nt
